# glu: the eight LDS operand reads of each output tile go through a 3-slot register ring with counted waits instead of one wait per read
# baseline (speedup 1.0000x reference)
.LBB0_298:
	v_ashrrev_i32_e32 v47, 31, v46
	v_lshlrev_b64 v[2:3], 9, v[46:47]
	v_lshl_add_u64 v[34:35], s[12:13], 0, v[2:3]
	v_lshl_add_u64 v[2:3], v[34:35], 0, v[0:1]
	global_load_dwordx4 v[30:33], v[2:3], off
	global_load_dwordx4 v[26:29], v[2:3], off offset:64
	global_load_dwordx4 v[22:25], v[2:3], off offset:128
	global_load_dwordx4 v[18:21], v[2:3], off offset:192
	global_load_dwordx4 v[14:17], v[2:3], off offset:256
	global_load_dwordx4 v[10:13], v[2:3], off offset:320
	global_load_dwordx4 v[6:9], v[2:3], off offset:384
	s_nop 0
	global_load_dwordx4 v[2:5], v[2:3], off offset:448
	v_mov_b32_e32 v49, v1
	v_lshl_add_u64 v[34:35], v[34:35], 0, v[48:49]
	global_load_dwordx2 v[82:83], v[34:35], off
	global_load_dwordx2 v[80:81], v[34:35], off offset:32
	global_load_dwordx2 v[78:79], v[34:35], off offset:64
	global_load_dwordx2 v[76:77], v[34:35], off offset:96
	global_load_dwordx2 v[74:75], v[34:35], off offset:128
	global_load_dwordx2 v[72:73], v[34:35], off offset:160
	global_load_dwordx2 v[70:71], v[34:35], off offset:192
	global_load_dwordx2 v[68:69], v[34:35], off offset:224
	global_load_dwordx2 v[66:67], v[34:35], off offset:256
	global_load_dwordx2 v[64:65], v[34:35], off offset:288
	global_load_dwordx2 v[62:63], v[34:35], off offset:320
	global_load_dwordx2 v[60:61], v[34:35], off offset:352
	global_load_dwordx2 v[58:59], v[34:35], off offset:384
	global_load_dwordx2 v[56:57], v[34:35], off offset:416
	global_load_dwordx2 v[54:55], v[34:35], off offset:448
	global_load_dwordx2 v[52:53], v[34:35], off offset:480
	v_lshlrev_b64 v[34:35], 11, v[46:47]
	v_lshl_add_u64 v[50:51], v[44:45], 0, v[34:35]
	global_load_dwordx4 v[34:37], v[42:43], off
	ds_read_b128 v[38:41], v85
	ds_read_b128 v[160:163], v85 offset:64
	ds_read_b128 v[150:153], v85 offset:128
	ds_read_b128 v[154:157], v85 offset:192
	v_add_u32_e32 v84, s1, v84
	s_movk_i32 s3, 0x83f
	v_add_u32_e32 v46, s2, v46
	s_waitcnt vmcnt(24) lgkmcnt(3)
	v_mfma_f32_16x16x32_bf16 v[38:41], v[38:41], v[30:33], 0
	s_waitcnt vmcnt(23) lgkmcnt(2)
	v_mfma_f32_16x16x32_bf16 v[38:41], v[160:163], v[26:29], v[38:41]
	ds_read_b128 v[160:163], v85 offset:256
	s_waitcnt vmcnt(22) lgkmcnt(2)
	v_mfma_f32_16x16x32_bf16 v[38:41], v[150:153], v[22:25], v[38:41]
	ds_read_b128 v[150:153], v85 offset:320
	s_waitcnt vmcnt(21) lgkmcnt(2)
	v_mfma_f32_16x16x32_bf16 v[38:41], v[154:157], v[18:21], v[38:41]
	ds_read_b128 v[154:157], v85 offset:384
	s_waitcnt vmcnt(20) lgkmcnt(2)
	v_mfma_f32_16x16x32_bf16 v[38:41], v[160:163], v[14:17], v[38:41]
	ds_read_b128 v[160:163], v85 offset:448
	s_waitcnt vmcnt(19) lgkmcnt(2)
	v_mfma_f32_16x16x32_bf16 v[38:41], v[150:153], v[10:13], v[38:41]
	s_waitcnt vmcnt(18) lgkmcnt(1)
	v_mfma_f32_16x16x32_bf16 v[38:41], v[154:157], v[6:9], v[38:41]
	s_waitcnt vmcnt(17) lgkmcnt(0)
	v_mfma_f32_16x16x32_bf16 v[38:41], v[160:163], v[2:5], v[38:41]
	s_waitcnt vmcnt(0)
	s_nop 6
	v_add_f32_e32 v34, v34, v38
	v_add_f32_e32 v35, v35, v39
	v_mul_f32_e32 v34, 0xbfb8aa3b, v34
	v_mul_f32_e32 v35, 0xbfb8aa3b, v35
	v_exp_f32_e32 v34, v34
	v_exp_f32_e32 v35, v35
	v_lshlrev_b32_e32 v38, 16, v82
	v_and_b32_e32 v39, 0xffff0000, v82
	v_pk_add_f32 v[34:35], v[34:35], 1.0 op_sel_hi:[1,0]
	s_nop 0
	v_rcp_f32_e32 v35, v35
	v_rcp_f32_e32 v34, v34
	s_nop 0
	v_pk_mul_f32 v[34:35], v[34:35], v[38:39]
	v_lshlrev_b32_e32 v38, 16, v83
	v_cvt_pk_bf16_f32 v34, v34, v35
	v_add_f32_e32 v35, v36, v40
	v_mul_f32_e32 v35, 0xbfb8aa3b, v35
	v_exp_f32_e32 v36, v35
	v_add_f32_e32 v35, v37, v41
	v_mul_f32_e32 v35, 0xbfb8aa3b, v35
	v_exp_f32_e32 v37, v35
	v_and_b32_e32 v39, 0xffff0000, v83
	v_pk_add_f32 v[36:37], v[36:37], 1.0 op_sel_hi:[1,0]
	s_nop 0
	v_rcp_f32_e32 v37, v37
	v_rcp_f32_e32 v36, v36
	s_nop 0
	v_pk_mul_f32 v[36:37], v[36:37], v[38:39]
	s_nop 0
	v_cvt_pk_bf16_f32 v35, v36, v37
	global_store_dwordx2 v[50:51], v[34:35], off
	ds_read_b128 v[38:41], v85 offset:8448
	ds_read_b128 v[160:163], v85 offset:8512
	ds_read_b128 v[150:153], v85 offset:8576
	ds_read_b128 v[154:157], v85 offset:8640
	s_waitcnt lgkmcnt(3)
	v_mfma_f32_16x16x32_bf16 v[38:41], v[38:41], v[30:33], 0
	s_waitcnt lgkmcnt(2)
	v_mfma_f32_16x16x32_bf16 v[38:41], v[160:163], v[26:29], v[38:41]
	ds_read_b128 v[160:163], v85 offset:8704
	s_waitcnt lgkmcnt(2)
	v_mfma_f32_16x16x32_bf16 v[38:41], v[150:153], v[22:25], v[38:41]
	ds_read_b128 v[150:153], v85 offset:8768
	s_waitcnt lgkmcnt(2)
	v_mfma_f32_16x16x32_bf16 v[38:41], v[154:157], v[18:21], v[38:41]
	ds_read_b128 v[154:157], v85 offset:8832
	s_waitcnt lgkmcnt(2)
	v_mfma_f32_16x16x32_bf16 v[38:41], v[160:163], v[14:17], v[38:41]
	ds_read_b128 v[160:163], v85 offset:8896
	s_waitcnt lgkmcnt(2)
	v_mfma_f32_16x16x32_bf16 v[38:41], v[150:153], v[10:13], v[38:41]
	s_waitcnt lgkmcnt(1)
	v_mfma_f32_16x16x32_bf16 v[38:41], v[154:157], v[6:9], v[38:41]
	s_waitcnt lgkmcnt(0)
	v_mfma_f32_16x16x32_bf16 v[38:41], v[160:163], v[2:5], v[38:41]
	s_nop 0
	s_nop 6
	v_add_f32_e32 v34, v164, v38
	v_add_f32_e32 v35, v165, v39
	v_mul_f32_e32 v34, 0xbfb8aa3b, v34
	v_mul_f32_e32 v35, 0xbfb8aa3b, v35
	v_exp_f32_e32 v34, v34
	v_exp_f32_e32 v35, v35
	v_lshlrev_b32_e32 v38, 16, v80
	v_and_b32_e32 v39, 0xffff0000, v80
	v_pk_add_f32 v[34:35], v[34:35], 1.0 op_sel_hi:[1,0]
	s_nop 0
	v_rcp_f32_e32 v35, v35
	v_rcp_f32_e32 v34, v34
	s_nop 0
	v_pk_mul_f32 v[34:35], v[34:35], v[38:39]
	v_lshlrev_b32_e32 v38, 16, v81
	v_cvt_pk_bf16_f32 v34, v34, v35
	v_add_f32_e32 v35, v166, v40
	v_mul_f32_e32 v35, 0xbfb8aa3b, v35
	v_exp_f32_e32 v36, v35
	v_add_f32_e32 v35, v167, v41
	v_mul_f32_e32 v35, 0xbfb8aa3b, v35
	v_exp_f32_e32 v37, v35
	v_and_b32_e32 v39, 0xffff0000, v81
	v_pk_add_f32 v[36:37], v[36:37], 1.0 op_sel_hi:[1,0]
	s_nop 0
	v_rcp_f32_e32 v37, v37
	v_rcp_f32_e32 v36, v36
	s_nop 0
	v_pk_mul_f32 v[36:37], v[36:37], v[38:39]
	s_nop 0
	v_cvt_pk_bf16_f32 v35, v36, v37
	global_store_dwordx2 v[50:51], v[34:35], off offset:32
	ds_read_b128 v[38:41], v85 offset:16896
	ds_read_b128 v[80:83], v85 offset:16960
	ds_read_b128 v[150:153], v85 offset:17024
	ds_read_b128 v[154:157], v85 offset:17088
	s_waitcnt lgkmcnt(3)
	v_mfma_f32_16x16x32_bf16 v[38:41], v[38:41], v[30:33], 0
	s_waitcnt lgkmcnt(2)
	v_mfma_f32_16x16x32_bf16 v[38:41], v[80:83], v[26:29], v[38:41]
	ds_read_b128 v[80:83], v85 offset:17152
	s_waitcnt lgkmcnt(2)
	v_mfma_f32_16x16x32_bf16 v[38:41], v[150:153], v[22:25], v[38:41]
	ds_read_b128 v[150:153], v85 offset:17216
	s_waitcnt lgkmcnt(2)
	v_mfma_f32_16x16x32_bf16 v[38:41], v[154:157], v[18:21], v[38:41]
	ds_read_b128 v[154:157], v85 offset:17280
	s_waitcnt lgkmcnt(2)
	v_mfma_f32_16x16x32_bf16 v[38:41], v[80:83], v[14:17], v[38:41]
	ds_read_b128 v[80:83], v85 offset:17344
	s_waitcnt lgkmcnt(2)
	v_mfma_f32_16x16x32_bf16 v[38:41], v[150:153], v[10:13], v[38:41]
	s_waitcnt lgkmcnt(1)
	v_mfma_f32_16x16x32_bf16 v[38:41], v[154:157], v[6:9], v[38:41]
	s_waitcnt lgkmcnt(0)
	v_mfma_f32_16x16x32_bf16 v[38:41], v[80:83], v[2:5], v[38:41]
	s_nop 0
	s_nop 6
	v_add_f32_e32 v34, v168, v38
	v_add_f32_e32 v35, v169, v39
	v_mul_f32_e32 v34, 0xbfb8aa3b, v34
	v_mul_f32_e32 v35, 0xbfb8aa3b, v35
	v_exp_f32_e32 v34, v34
	v_exp_f32_e32 v35, v35
	v_lshlrev_b32_e32 v38, 16, v78
	v_and_b32_e32 v39, 0xffff0000, v78
	v_pk_add_f32 v[34:35], v[34:35], 1.0 op_sel_hi:[1,0]
	s_nop 0
	v_rcp_f32_e32 v35, v35
	v_rcp_f32_e32 v34, v34
	s_nop 0
	v_pk_mul_f32 v[34:35], v[34:35], v[38:39]
	v_lshlrev_b32_e32 v38, 16, v79
	v_cvt_pk_bf16_f32 v34, v34, v35
	v_add_f32_e32 v35, v170, v40
	v_mul_f32_e32 v35, 0xbfb8aa3b, v35
	v_exp_f32_e32 v36, v35
	v_add_f32_e32 v35, v171, v41
	v_mul_f32_e32 v35, 0xbfb8aa3b, v35
	v_exp_f32_e32 v37, v35
	v_and_b32_e32 v39, 0xffff0000, v79
	v_pk_add_f32 v[36:37], v[36:37], 1.0 op_sel_hi:[1,0]
	s_nop 0
	v_rcp_f32_e32 v37, v37
	v_rcp_f32_e32 v36, v36
	s_nop 0
	v_pk_mul_f32 v[36:37], v[36:37], v[38:39]
	s_nop 0
	v_cvt_pk_bf16_f32 v35, v36, v37
	global_store_dwordx2 v[50:51], v[34:35], off offset:64
	ds_read_b128 v[38:41], v85 offset:25344
	ds_read_b128 v[78:81], v85 offset:25408
	ds_read_b128 v[150:153], v85 offset:25472
	ds_read_b128 v[154:157], v85 offset:25536
	s_waitcnt lgkmcnt(3)
	v_mfma_f32_16x16x32_bf16 v[38:41], v[38:41], v[30:33], 0
	s_waitcnt lgkmcnt(2)
	v_mfma_f32_16x16x32_bf16 v[38:41], v[78:81], v[26:29], v[38:41]
	ds_read_b128 v[78:81], v85 offset:25600
	s_waitcnt lgkmcnt(2)
	v_mfma_f32_16x16x32_bf16 v[38:41], v[150:153], v[22:25], v[38:41]
	ds_read_b128 v[150:153], v85 offset:25664
	s_waitcnt lgkmcnt(2)
	v_mfma_f32_16x16x32_bf16 v[38:41], v[154:157], v[18:21], v[38:41]
	ds_read_b128 v[154:157], v85 offset:25728
	s_waitcnt lgkmcnt(2)
	v_mfma_f32_16x16x32_bf16 v[38:41], v[78:81], v[14:17], v[38:41]
	ds_read_b128 v[78:81], v85 offset:25792
	s_waitcnt lgkmcnt(2)
	v_mfma_f32_16x16x32_bf16 v[38:41], v[150:153], v[10:13], v[38:41]
	s_waitcnt lgkmcnt(1)
	v_mfma_f32_16x16x32_bf16 v[38:41], v[154:157], v[6:9], v[38:41]
	s_waitcnt lgkmcnt(0)
	v_mfma_f32_16x16x32_bf16 v[38:41], v[78:81], v[2:5], v[38:41]
	s_nop 0
	s_nop 6
	v_add_f32_e32 v34, v172, v38
	v_add_f32_e32 v35, v173, v39
	v_mul_f32_e32 v34, 0xbfb8aa3b, v34
	v_mul_f32_e32 v35, 0xbfb8aa3b, v35
	v_exp_f32_e32 v34, v34
	v_exp_f32_e32 v35, v35
	v_lshlrev_b32_e32 v38, 16, v76
	v_and_b32_e32 v39, 0xffff0000, v76
	v_pk_add_f32 v[34:35], v[34:35], 1.0 op_sel_hi:[1,0]
	s_nop 0
	v_rcp_f32_e32 v35, v35
	v_rcp_f32_e32 v34, v34
	s_nop 0
	v_pk_mul_f32 v[34:35], v[34:35], v[38:39]
	v_lshlrev_b32_e32 v38, 16, v77
	v_cvt_pk_bf16_f32 v34, v34, v35
	v_add_f32_e32 v35, v174, v40
	v_mul_f32_e32 v35, 0xbfb8aa3b, v35
	v_exp_f32_e32 v36, v35
	v_add_f32_e32 v35, v175, v41
	v_mul_f32_e32 v35, 0xbfb8aa3b, v35
	v_exp_f32_e32 v37, v35
	v_and_b32_e32 v39, 0xffff0000, v77
	v_pk_add_f32 v[36:37], v[36:37], 1.0 op_sel_hi:[1,0]
	s_nop 0
	v_rcp_f32_e32 v37, v37
	v_rcp_f32_e32 v36, v36
	s_nop 0
	v_pk_mul_f32 v[36:37], v[36:37], v[38:39]
	s_nop 0
	v_cvt_pk_bf16_f32 v35, v36, v37
	global_store_dwordx2 v[50:51], v[34:35], off offset:96
	ds_read_b128 v[38:41], v85 offset:33792
	ds_read_b128 v[76:79], v85 offset:33856
	ds_read_b128 v[150:153], v85 offset:33920
	ds_read_b128 v[154:157], v85 offset:33984
	s_waitcnt lgkmcnt(3)
	v_mfma_f32_16x16x32_bf16 v[38:41], v[38:41], v[30:33], 0
	s_waitcnt lgkmcnt(2)
	v_mfma_f32_16x16x32_bf16 v[38:41], v[76:79], v[26:29], v[38:41]
	ds_read_b128 v[76:79], v85 offset:34048
	s_waitcnt lgkmcnt(2)
	v_mfma_f32_16x16x32_bf16 v[38:41], v[150:153], v[22:25], v[38:41]
	ds_read_b128 v[150:153], v85 offset:34112
	s_waitcnt lgkmcnt(2)
	v_mfma_f32_16x16x32_bf16 v[38:41], v[154:157], v[18:21], v[38:41]
	ds_read_b128 v[154:157], v85 offset:34176
	s_waitcnt lgkmcnt(2)
	v_mfma_f32_16x16x32_bf16 v[38:41], v[76:79], v[14:17], v[38:41]
	ds_read_b128 v[76:79], v85 offset:34240
	s_waitcnt lgkmcnt(2)
	v_mfma_f32_16x16x32_bf16 v[38:41], v[150:153], v[10:13], v[38:41]
	s_waitcnt lgkmcnt(1)
	v_mfma_f32_16x16x32_bf16 v[38:41], v[154:157], v[6:9], v[38:41]
	s_waitcnt lgkmcnt(0)
	v_mfma_f32_16x16x32_bf16 v[38:41], v[76:79], v[2:5], v[38:41]
	s_nop 0
	s_nop 6
	v_add_f32_e32 v34, v176, v38
	v_add_f32_e32 v35, v177, v39
	v_mul_f32_e32 v34, 0xbfb8aa3b, v34
	v_mul_f32_e32 v35, 0xbfb8aa3b, v35
	v_exp_f32_e32 v34, v34
	v_exp_f32_e32 v35, v35
	v_lshlrev_b32_e32 v38, 16, v74
	v_and_b32_e32 v39, 0xffff0000, v74
	v_pk_add_f32 v[34:35], v[34:35], 1.0 op_sel_hi:[1,0]
	s_nop 0
	v_rcp_f32_e32 v35, v35
	v_rcp_f32_e32 v34, v34
	s_nop 0
	v_pk_mul_f32 v[34:35], v[34:35], v[38:39]
	v_lshlrev_b32_e32 v38, 16, v75
	v_cvt_pk_bf16_f32 v34, v34, v35
	v_add_f32_e32 v35, v178, v40
	v_mul_f32_e32 v35, 0xbfb8aa3b, v35
	v_exp_f32_e32 v36, v35
	v_add_f32_e32 v35, v179, v41
	v_mul_f32_e32 v35, 0xbfb8aa3b, v35
	v_exp_f32_e32 v37, v35
	v_and_b32_e32 v39, 0xffff0000, v75
	v_pk_add_f32 v[36:37], v[36:37], 1.0 op_sel_hi:[1,0]
	s_nop 0
	v_rcp_f32_e32 v37, v37
	v_rcp_f32_e32 v36, v36
	s_nop 0
	v_pk_mul_f32 v[36:37], v[36:37], v[38:39]
	s_nop 0
	v_cvt_pk_bf16_f32 v35, v36, v37
	global_store_dwordx2 v[50:51], v[34:35], off offset:128
	ds_read_b128 v[38:41], v85 offset:42240
	ds_read_b128 v[74:77], v85 offset:42304
	ds_read_b128 v[150:153], v85 offset:42368
	ds_read_b128 v[154:157], v85 offset:42432
	s_waitcnt lgkmcnt(3)
	v_mfma_f32_16x16x32_bf16 v[38:41], v[38:41], v[30:33], 0
	s_waitcnt lgkmcnt(2)
	v_mfma_f32_16x16x32_bf16 v[38:41], v[74:77], v[26:29], v[38:41]
	ds_read_b128 v[74:77], v85 offset:42496
	s_waitcnt lgkmcnt(2)
	v_mfma_f32_16x16x32_bf16 v[38:41], v[150:153], v[22:25], v[38:41]
	ds_read_b128 v[150:153], v85 offset:42560
	s_waitcnt lgkmcnt(2)
	v_mfma_f32_16x16x32_bf16 v[38:41], v[154:157], v[18:21], v[38:41]
	ds_read_b128 v[154:157], v85 offset:42624
	s_waitcnt lgkmcnt(2)
	v_mfma_f32_16x16x32_bf16 v[38:41], v[74:77], v[14:17], v[38:41]
	ds_read_b128 v[74:77], v85 offset:42688
	s_waitcnt lgkmcnt(2)
	v_mfma_f32_16x16x32_bf16 v[38:41], v[150:153], v[10:13], v[38:41]
	s_waitcnt lgkmcnt(1)
	v_mfma_f32_16x16x32_bf16 v[38:41], v[154:157], v[6:9], v[38:41]
	s_waitcnt lgkmcnt(0)
	v_mfma_f32_16x16x32_bf16 v[38:41], v[74:77], v[2:5], v[38:41]
	s_nop 0
	s_nop 6
	v_add_f32_e32 v34, v180, v38
	v_add_f32_e32 v35, v181, v39
	v_mul_f32_e32 v34, 0xbfb8aa3b, v34
	v_mul_f32_e32 v35, 0xbfb8aa3b, v35
	v_exp_f32_e32 v34, v34
	v_exp_f32_e32 v35, v35
	v_lshlrev_b32_e32 v38, 16, v72
	v_and_b32_e32 v39, 0xffff0000, v72
	v_pk_add_f32 v[34:35], v[34:35], 1.0 op_sel_hi:[1,0]
	s_nop 0
	v_rcp_f32_e32 v35, v35
	v_rcp_f32_e32 v34, v34
	s_nop 0
	v_pk_mul_f32 v[34:35], v[34:35], v[38:39]
	v_lshlrev_b32_e32 v38, 16, v73
	v_cvt_pk_bf16_f32 v34, v34, v35
	v_add_f32_e32 v35, v182, v40
	v_mul_f32_e32 v35, 0xbfb8aa3b, v35
	v_exp_f32_e32 v36, v35
	v_add_f32_e32 v35, v183, v41
	v_mul_f32_e32 v35, 0xbfb8aa3b, v35
	v_exp_f32_e32 v37, v35
	v_and_b32_e32 v39, 0xffff0000, v73
	v_pk_add_f32 v[36:37], v[36:37], 1.0 op_sel_hi:[1,0]
	s_nop 0
	v_rcp_f32_e32 v37, v37
	v_rcp_f32_e32 v36, v36
	s_nop 0
	v_pk_mul_f32 v[36:37], v[36:37], v[38:39]
	s_nop 0
	v_cvt_pk_bf16_f32 v35, v36, v37
	global_store_dwordx2 v[50:51], v[34:35], off offset:160
	ds_read_b128 v[38:41], v85 offset:50688
	ds_read_b128 v[72:75], v85 offset:50752
	ds_read_b128 v[150:153], v85 offset:50816
	ds_read_b128 v[154:157], v85 offset:50880
	s_waitcnt lgkmcnt(3)
	v_mfma_f32_16x16x32_bf16 v[38:41], v[38:41], v[30:33], 0
	s_waitcnt lgkmcnt(2)
	v_mfma_f32_16x16x32_bf16 v[38:41], v[72:75], v[26:29], v[38:41]
	ds_read_b128 v[72:75], v85 offset:50944
	s_waitcnt lgkmcnt(2)
	v_mfma_f32_16x16x32_bf16 v[38:41], v[150:153], v[22:25], v[38:41]
	ds_read_b128 v[150:153], v85 offset:51008
	s_waitcnt lgkmcnt(2)
	v_mfma_f32_16x16x32_bf16 v[38:41], v[154:157], v[18:21], v[38:41]
	ds_read_b128 v[154:157], v85 offset:51072
	s_waitcnt lgkmcnt(2)
	v_mfma_f32_16x16x32_bf16 v[38:41], v[72:75], v[14:17], v[38:41]
	ds_read_b128 v[72:75], v85 offset:51136
	s_waitcnt lgkmcnt(2)
	v_mfma_f32_16x16x32_bf16 v[38:41], v[150:153], v[10:13], v[38:41]
	s_waitcnt lgkmcnt(1)
	v_mfma_f32_16x16x32_bf16 v[38:41], v[154:157], v[6:9], v[38:41]
	s_waitcnt lgkmcnt(0)
	v_mfma_f32_16x16x32_bf16 v[38:41], v[72:75], v[2:5], v[38:41]
	s_nop 0
	s_nop 6
	v_add_f32_e32 v34, v184, v38
	v_add_f32_e32 v35, v185, v39
	v_mul_f32_e32 v34, 0xbfb8aa3b, v34
	v_mul_f32_e32 v35, 0xbfb8aa3b, v35
	v_exp_f32_e32 v34, v34
	v_exp_f32_e32 v35, v35
	v_lshlrev_b32_e32 v38, 16, v70
	v_and_b32_e32 v39, 0xffff0000, v70
	v_pk_add_f32 v[34:35], v[34:35], 1.0 op_sel_hi:[1,0]
	s_nop 0
	v_rcp_f32_e32 v35, v35
	v_rcp_f32_e32 v34, v34
	s_nop 0
	v_pk_mul_f32 v[34:35], v[34:35], v[38:39]
	v_lshlrev_b32_e32 v38, 16, v71
	v_cvt_pk_bf16_f32 v34, v34, v35
	v_add_f32_e32 v35, v186, v40
	v_mul_f32_e32 v35, 0xbfb8aa3b, v35
	v_exp_f32_e32 v36, v35
	v_add_f32_e32 v35, v187, v41
	v_mul_f32_e32 v35, 0xbfb8aa3b, v35
	v_exp_f32_e32 v37, v35
	v_and_b32_e32 v39, 0xffff0000, v71
	v_pk_add_f32 v[36:37], v[36:37], 1.0 op_sel_hi:[1,0]
	s_nop 0
	v_rcp_f32_e32 v37, v37
	v_rcp_f32_e32 v36, v36
	s_nop 0
	v_pk_mul_f32 v[36:37], v[36:37], v[38:39]
	s_nop 0
	v_cvt_pk_bf16_f32 v35, v36, v37
	global_store_dwordx2 v[50:51], v[34:35], off offset:192
	ds_read_b128 v[38:41], v85 offset:59136
	ds_read_b128 v[70:73], v85 offset:59200
	ds_read_b128 v[150:153], v85 offset:59264
	ds_read_b128 v[154:157], v85 offset:59328
	s_waitcnt lgkmcnt(3)
	v_mfma_f32_16x16x32_bf16 v[38:41], v[38:41], v[30:33], 0
	s_waitcnt lgkmcnt(2)
	v_mfma_f32_16x16x32_bf16 v[38:41], v[70:73], v[26:29], v[38:41]
	ds_read_b128 v[70:73], v85 offset:59392
	s_waitcnt lgkmcnt(2)
	v_mfma_f32_16x16x32_bf16 v[38:41], v[150:153], v[22:25], v[38:41]
	ds_read_b128 v[150:153], v85 offset:59456
	s_waitcnt lgkmcnt(2)
	v_mfma_f32_16x16x32_bf16 v[38:41], v[154:157], v[18:21], v[38:41]
	ds_read_b128 v[154:157], v85 offset:59520
	s_waitcnt lgkmcnt(2)
	v_mfma_f32_16x16x32_bf16 v[38:41], v[70:73], v[14:17], v[38:41]
	ds_read_b128 v[70:73], v85 offset:59584
	s_waitcnt lgkmcnt(2)
	v_mfma_f32_16x16x32_bf16 v[38:41], v[150:153], v[10:13], v[38:41]
	s_waitcnt lgkmcnt(1)
	v_mfma_f32_16x16x32_bf16 v[38:41], v[154:157], v[6:9], v[38:41]
	s_waitcnt lgkmcnt(0)
	v_mfma_f32_16x16x32_bf16 v[38:41], v[70:73], v[2:5], v[38:41]
	s_nop 0
	s_nop 6
	v_add_f32_e32 v34, v188, v38
	v_add_f32_e32 v35, v189, v39
	v_mul_f32_e32 v34, 0xbfb8aa3b, v34
	v_mul_f32_e32 v35, 0xbfb8aa3b, v35
	v_exp_f32_e32 v34, v34
	v_exp_f32_e32 v35, v35
	v_lshlrev_b32_e32 v38, 16, v68
	v_and_b32_e32 v39, 0xffff0000, v68
	v_pk_add_f32 v[34:35], v[34:35], 1.0 op_sel_hi:[1,0]
	s_nop 0
	v_rcp_f32_e32 v35, v35
	v_rcp_f32_e32 v34, v34
	s_nop 0
	v_pk_mul_f32 v[34:35], v[34:35], v[38:39]
	v_lshlrev_b32_e32 v38, 16, v69
	v_cvt_pk_bf16_f32 v34, v34, v35
	v_add_f32_e32 v35, v190, v40
	v_mul_f32_e32 v35, 0xbfb8aa3b, v35
	v_exp_f32_e32 v36, v35
	v_add_f32_e32 v35, v191, v41
	v_mul_f32_e32 v35, 0xbfb8aa3b, v35
	v_exp_f32_e32 v37, v35
	v_and_b32_e32 v39, 0xffff0000, v69
	v_pk_add_f32 v[36:37], v[36:37], 1.0 op_sel_hi:[1,0]
	s_nop 0
	v_rcp_f32_e32 v37, v37
	v_rcp_f32_e32 v36, v36
	s_nop 0
	v_pk_mul_f32 v[36:37], v[36:37], v[38:39]
	s_nop 0
	v_cvt_pk_bf16_f32 v35, v36, v37
	global_store_dwordx2 v[50:51], v[34:35], off offset:224
	ds_read_b128 v[38:41], v86
	ds_read_b128 v[68:71], v87
	ds_read_b128 v[150:153], v88
	ds_read_b128 v[154:157], v89
	s_waitcnt lgkmcnt(3)
	v_mfma_f32_16x16x32_bf16 v[38:41], v[38:41], v[30:33], 0
	s_waitcnt lgkmcnt(2)
	v_mfma_f32_16x16x32_bf16 v[38:41], v[68:71], v[26:29], v[38:41]
	ds_read_b128 v[68:71], v90
	s_waitcnt lgkmcnt(2)
	v_mfma_f32_16x16x32_bf16 v[38:41], v[150:153], v[22:25], v[38:41]
	ds_read_b128 v[150:153], v91
	s_waitcnt lgkmcnt(2)
	v_mfma_f32_16x16x32_bf16 v[38:41], v[154:157], v[18:21], v[38:41]
	ds_read_b128 v[154:157], v92
	s_waitcnt lgkmcnt(2)
	v_mfma_f32_16x16x32_bf16 v[38:41], v[68:71], v[14:17], v[38:41]
	ds_read_b128 v[68:71], v93
	s_waitcnt lgkmcnt(2)
	v_mfma_f32_16x16x32_bf16 v[38:41], v[150:153], v[10:13], v[38:41]
	s_waitcnt lgkmcnt(1)
	v_mfma_f32_16x16x32_bf16 v[38:41], v[154:157], v[6:9], v[38:41]
	s_waitcnt lgkmcnt(0)
	v_mfma_f32_16x16x32_bf16 v[38:41], v[68:71], v[2:5], v[38:41]
	s_nop 0
	s_nop 6
	v_add_f32_e32 v34, v192, v38
	v_add_f32_e32 v35, v193, v39
	v_mul_f32_e32 v34, 0xbfb8aa3b, v34
	v_mul_f32_e32 v35, 0xbfb8aa3b, v35
	v_exp_f32_e32 v34, v34
	v_exp_f32_e32 v35, v35
	v_lshlrev_b32_e32 v38, 16, v66
	v_and_b32_e32 v39, 0xffff0000, v66
	v_pk_add_f32 v[34:35], v[34:35], 1.0 op_sel_hi:[1,0]
	s_nop 0
	v_rcp_f32_e32 v35, v35
	v_rcp_f32_e32 v34, v34
	s_nop 0
	v_pk_mul_f32 v[34:35], v[34:35], v[38:39]
	v_lshlrev_b32_e32 v38, 16, v67
	v_cvt_pk_bf16_f32 v34, v34, v35
	v_add_f32_e32 v35, v194, v40
	v_mul_f32_e32 v35, 0xbfb8aa3b, v35
	v_exp_f32_e32 v36, v35
	v_add_f32_e32 v35, v195, v41
	v_mul_f32_e32 v35, 0xbfb8aa3b, v35
	v_exp_f32_e32 v37, v35
	v_and_b32_e32 v39, 0xffff0000, v67
	v_pk_add_f32 v[36:37], v[36:37], 1.0 op_sel_hi:[1,0]
	s_nop 0
	v_rcp_f32_e32 v37, v37
	v_rcp_f32_e32 v36, v36
	s_nop 0
	v_pk_mul_f32 v[36:37], v[36:37], v[38:39]
	s_nop 0
	v_cvt_pk_bf16_f32 v35, v36, v37
	global_store_dwordx2 v[50:51], v[34:35], off offset:256
	ds_read_b128 v[38:41], v94
	ds_read_b128 v[66:69], v95
	ds_read_b128 v[150:153], v96
	ds_read_b128 v[154:157], v97
	s_waitcnt lgkmcnt(3)
	v_mfma_f32_16x16x32_bf16 v[38:41], v[38:41], v[30:33], 0
	s_waitcnt lgkmcnt(2)
	v_mfma_f32_16x16x32_bf16 v[38:41], v[66:69], v[26:29], v[38:41]
	ds_read_b128 v[66:69], v98
	s_waitcnt lgkmcnt(2)
	v_mfma_f32_16x16x32_bf16 v[38:41], v[150:153], v[22:25], v[38:41]
	ds_read_b128 v[150:153], v99
	s_waitcnt lgkmcnt(2)
	v_mfma_f32_16x16x32_bf16 v[38:41], v[154:157], v[18:21], v[38:41]
	ds_read_b128 v[154:157], v100
	s_waitcnt lgkmcnt(2)
	v_mfma_f32_16x16x32_bf16 v[38:41], v[66:69], v[14:17], v[38:41]
	ds_read_b128 v[66:69], v101
	s_waitcnt lgkmcnt(2)
	v_mfma_f32_16x16x32_bf16 v[38:41], v[150:153], v[10:13], v[38:41]
	s_waitcnt lgkmcnt(1)
	v_mfma_f32_16x16x32_bf16 v[38:41], v[154:157], v[6:9], v[38:41]
	s_waitcnt lgkmcnt(0)
	v_mfma_f32_16x16x32_bf16 v[38:41], v[66:69], v[2:5], v[38:41]
	s_nop 0
	s_nop 6
	v_add_f32_e32 v34, v196, v38
	v_add_f32_e32 v35, v197, v39
	v_mul_f32_e32 v34, 0xbfb8aa3b, v34
	v_mul_f32_e32 v35, 0xbfb8aa3b, v35
	v_exp_f32_e32 v34, v34
	v_exp_f32_e32 v35, v35
	v_lshlrev_b32_e32 v38, 16, v64
	v_and_b32_e32 v39, 0xffff0000, v64
	v_pk_add_f32 v[34:35], v[34:35], 1.0 op_sel_hi:[1,0]
	s_nop 0
	v_rcp_f32_e32 v35, v35
	v_rcp_f32_e32 v34, v34
	s_nop 0
	v_pk_mul_f32 v[34:35], v[34:35], v[38:39]
	v_lshlrev_b32_e32 v38, 16, v65
	v_cvt_pk_bf16_f32 v34, v34, v35
	v_add_f32_e32 v35, v198, v40
	v_mul_f32_e32 v35, 0xbfb8aa3b, v35
	v_exp_f32_e32 v36, v35
	v_add_f32_e32 v35, v199, v41
	v_mul_f32_e32 v35, 0xbfb8aa3b, v35
	v_exp_f32_e32 v37, v35
	v_and_b32_e32 v39, 0xffff0000, v65
	v_pk_add_f32 v[36:37], v[36:37], 1.0 op_sel_hi:[1,0]
	s_nop 0
	v_rcp_f32_e32 v37, v37
	v_rcp_f32_e32 v36, v36
	s_nop 0
	v_pk_mul_f32 v[36:37], v[36:37], v[38:39]
	s_nop 0
	v_cvt_pk_bf16_f32 v35, v36, v37
	global_store_dwordx2 v[50:51], v[34:35], off offset:288
	ds_read_b128 v[38:41], v102
	ds_read_b128 v[64:67], v103
	ds_read_b128 v[150:153], v104
	ds_read_b128 v[154:157], v105
	s_waitcnt lgkmcnt(3)
	v_mfma_f32_16x16x32_bf16 v[38:41], v[38:41], v[30:33], 0
	s_waitcnt lgkmcnt(2)
	v_mfma_f32_16x16x32_bf16 v[38:41], v[64:67], v[26:29], v[38:41]
	ds_read_b128 v[64:67], v106
	s_waitcnt lgkmcnt(2)
	v_mfma_f32_16x16x32_bf16 v[38:41], v[150:153], v[22:25], v[38:41]
	ds_read_b128 v[150:153], v107
	s_waitcnt lgkmcnt(2)
	v_mfma_f32_16x16x32_bf16 v[38:41], v[154:157], v[18:21], v[38:41]
	ds_read_b128 v[154:157], v108
	s_waitcnt lgkmcnt(2)
	v_mfma_f32_16x16x32_bf16 v[38:41], v[64:67], v[14:17], v[38:41]
	ds_read_b128 v[64:67], v109
	s_waitcnt lgkmcnt(2)
	v_mfma_f32_16x16x32_bf16 v[38:41], v[150:153], v[10:13], v[38:41]
	s_waitcnt lgkmcnt(1)
	v_mfma_f32_16x16x32_bf16 v[38:41], v[154:157], v[6:9], v[38:41]
	s_waitcnt lgkmcnt(0)
	v_mfma_f32_16x16x32_bf16 v[38:41], v[64:67], v[2:5], v[38:41]
	s_nop 0
	s_nop 6
	v_add_f32_e32 v34, v200, v38
	v_add_f32_e32 v35, v201, v39
	v_mul_f32_e32 v34, 0xbfb8aa3b, v34
	v_mul_f32_e32 v35, 0xbfb8aa3b, v35
	v_exp_f32_e32 v34, v34
	v_exp_f32_e32 v35, v35
	v_lshlrev_b32_e32 v38, 16, v62
	v_and_b32_e32 v39, 0xffff0000, v62
	v_pk_add_f32 v[34:35], v[34:35], 1.0 op_sel_hi:[1,0]
	s_nop 0
	v_rcp_f32_e32 v35, v35
	v_rcp_f32_e32 v34, v34
	s_nop 0
	v_pk_mul_f32 v[34:35], v[34:35], v[38:39]
	v_lshlrev_b32_e32 v38, 16, v63
	v_cvt_pk_bf16_f32 v34, v34, v35
	v_add_f32_e32 v35, v202, v40
	v_mul_f32_e32 v35, 0xbfb8aa3b, v35
	v_exp_f32_e32 v36, v35
	v_add_f32_e32 v35, v203, v41
	v_mul_f32_e32 v35, 0xbfb8aa3b, v35
	v_exp_f32_e32 v37, v35
	v_and_b32_e32 v39, 0xffff0000, v63
	v_pk_add_f32 v[36:37], v[36:37], 1.0 op_sel_hi:[1,0]
	s_nop 0
	v_rcp_f32_e32 v37, v37
	v_rcp_f32_e32 v36, v36
	s_nop 0
	v_pk_mul_f32 v[36:37], v[36:37], v[38:39]
	s_nop 0
	v_cvt_pk_bf16_f32 v35, v36, v37
	global_store_dwordx2 v[50:51], v[34:35], off offset:320
	ds_read_b128 v[38:41], v110
	ds_read_b128 v[62:65], v111
	ds_read_b128 v[150:153], v112
	ds_read_b128 v[154:157], v113
	s_waitcnt lgkmcnt(3)
	v_mfma_f32_16x16x32_bf16 v[38:41], v[38:41], v[30:33], 0
	s_waitcnt lgkmcnt(2)
	v_mfma_f32_16x16x32_bf16 v[38:41], v[62:65], v[26:29], v[38:41]
	ds_read_b128 v[62:65], v114
	s_waitcnt lgkmcnt(2)
	v_mfma_f32_16x16x32_bf16 v[38:41], v[150:153], v[22:25], v[38:41]
	ds_read_b128 v[150:153], v115
	s_waitcnt lgkmcnt(2)
	v_mfma_f32_16x16x32_bf16 v[38:41], v[154:157], v[18:21], v[38:41]
	ds_read_b128 v[154:157], v116
	s_waitcnt lgkmcnt(2)
	v_mfma_f32_16x16x32_bf16 v[38:41], v[62:65], v[14:17], v[38:41]
	ds_read_b128 v[62:65], v117
	s_waitcnt lgkmcnt(2)
	v_mfma_f32_16x16x32_bf16 v[38:41], v[150:153], v[10:13], v[38:41]
	s_waitcnt lgkmcnt(1)
	v_mfma_f32_16x16x32_bf16 v[38:41], v[154:157], v[6:9], v[38:41]
	s_waitcnt lgkmcnt(0)
	v_mfma_f32_16x16x32_bf16 v[38:41], v[62:65], v[2:5], v[38:41]
	s_nop 0
	s_nop 6
	v_add_f32_e32 v34, v234, v38
	v_add_f32_e32 v35, v235, v39
	v_mul_f32_e32 v34, 0xbfb8aa3b, v34
	v_mul_f32_e32 v35, 0xbfb8aa3b, v35
	v_exp_f32_e32 v34, v34
	v_exp_f32_e32 v35, v35
	v_lshlrev_b32_e32 v38, 16, v60
	v_and_b32_e32 v39, 0xffff0000, v60
	v_pk_add_f32 v[34:35], v[34:35], 1.0 op_sel_hi:[1,0]
	s_nop 0
	v_rcp_f32_e32 v35, v35
	v_rcp_f32_e32 v34, v34
	s_nop 0
	v_pk_mul_f32 v[34:35], v[34:35], v[38:39]
	v_lshlrev_b32_e32 v38, 16, v61
	v_cvt_pk_bf16_f32 v34, v34, v35
	v_add_f32_e32 v35, v236, v40
	v_mul_f32_e32 v35, 0xbfb8aa3b, v35
	v_exp_f32_e32 v36, v35
	v_add_f32_e32 v35, v237, v41
	v_mul_f32_e32 v35, 0xbfb8aa3b, v35
	v_exp_f32_e32 v37, v35
	v_and_b32_e32 v39, 0xffff0000, v61
	v_pk_add_f32 v[36:37], v[36:37], 1.0 op_sel_hi:[1,0]
	s_nop 0
	v_rcp_f32_e32 v37, v37
	v_rcp_f32_e32 v36, v36
	s_nop 0
	v_pk_mul_f32 v[36:37], v[36:37], v[38:39]
	s_nop 0
	v_cvt_pk_bf16_f32 v35, v36, v37
	global_store_dwordx2 v[50:51], v[34:35], off offset:352
	ds_read_b128 v[38:41], v118
	ds_read_b128 v[60:63], v119
	ds_read_b128 v[150:153], v120
	ds_read_b128 v[154:157], v121
	s_waitcnt lgkmcnt(3)
	v_mfma_f32_16x16x32_bf16 v[38:41], v[38:41], v[30:33], 0
	s_waitcnt lgkmcnt(2)
	v_mfma_f32_16x16x32_bf16 v[38:41], v[60:63], v[26:29], v[38:41]
	ds_read_b128 v[60:63], v122
	s_waitcnt lgkmcnt(2)
	v_mfma_f32_16x16x32_bf16 v[38:41], v[150:153], v[22:25], v[38:41]
	ds_read_b128 v[150:153], v123
	s_waitcnt lgkmcnt(2)
	v_mfma_f32_16x16x32_bf16 v[38:41], v[154:157], v[18:21], v[38:41]
	ds_read_b128 v[154:157], v124
	s_waitcnt lgkmcnt(2)
	v_mfma_f32_16x16x32_bf16 v[38:41], v[60:63], v[14:17], v[38:41]
	ds_read_b128 v[60:63], v125
	s_waitcnt lgkmcnt(2)
	v_mfma_f32_16x16x32_bf16 v[38:41], v[150:153], v[10:13], v[38:41]
	s_waitcnt lgkmcnt(1)
	v_mfma_f32_16x16x32_bf16 v[38:41], v[154:157], v[6:9], v[38:41]
	s_waitcnt lgkmcnt(0)
	v_mfma_f32_16x16x32_bf16 v[38:41], v[60:63], v[2:5], v[38:41]
	s_nop 0
	s_nop 6
	v_add_f32_e32 v34, v238, v38
	v_add_f32_e32 v35, v239, v39
	v_mul_f32_e32 v34, 0xbfb8aa3b, v34
	v_mul_f32_e32 v35, 0xbfb8aa3b, v35
	v_exp_f32_e32 v34, v34
	v_exp_f32_e32 v35, v35
	v_lshlrev_b32_e32 v38, 16, v58
	v_and_b32_e32 v39, 0xffff0000, v58
	v_pk_add_f32 v[34:35], v[34:35], 1.0 op_sel_hi:[1,0]
	s_nop 0
	v_rcp_f32_e32 v35, v35
	v_rcp_f32_e32 v34, v34
	s_nop 0
	v_pk_mul_f32 v[34:35], v[34:35], v[38:39]
	v_lshlrev_b32_e32 v38, 16, v59
	v_cvt_pk_bf16_f32 v34, v34, v35
	v_add_f32_e32 v35, v240, v40
	v_mul_f32_e32 v35, 0xbfb8aa3b, v35
	v_exp_f32_e32 v36, v35
	v_add_f32_e32 v35, v241, v41
	v_mul_f32_e32 v35, 0xbfb8aa3b, v35
	v_exp_f32_e32 v37, v35
	v_and_b32_e32 v39, 0xffff0000, v59
	v_pk_add_f32 v[36:37], v[36:37], 1.0 op_sel_hi:[1,0]
	s_nop 0
	v_rcp_f32_e32 v37, v37
	v_rcp_f32_e32 v36, v36
	s_nop 0
	v_pk_mul_f32 v[36:37], v[36:37], v[38:39]
	s_nop 0
	v_cvt_pk_bf16_f32 v35, v36, v37
	global_store_dwordx2 v[50:51], v[34:35], off offset:384
	ds_read_b128 v[38:41], v126
	ds_read_b128 v[58:61], v127
	ds_read_b128 v[150:153], v128
	ds_read_b128 v[154:157], v129
	s_waitcnt lgkmcnt(3)
	v_mfma_f32_16x16x32_bf16 v[38:41], v[38:41], v[30:33], 0
	s_waitcnt lgkmcnt(2)
	v_mfma_f32_16x16x32_bf16 v[38:41], v[58:61], v[26:29], v[38:41]
	ds_read_b128 v[58:61], v130
	s_waitcnt lgkmcnt(2)
	v_mfma_f32_16x16x32_bf16 v[38:41], v[150:153], v[22:25], v[38:41]
	ds_read_b128 v[150:153], v131
	s_waitcnt lgkmcnt(2)
	v_mfma_f32_16x16x32_bf16 v[38:41], v[154:157], v[18:21], v[38:41]
	ds_read_b128 v[154:157], v132
	s_waitcnt lgkmcnt(2)
	v_mfma_f32_16x16x32_bf16 v[38:41], v[58:61], v[14:17], v[38:41]
	ds_read_b128 v[58:61], v133
	s_waitcnt lgkmcnt(2)
	v_mfma_f32_16x16x32_bf16 v[38:41], v[150:153], v[10:13], v[38:41]
	s_waitcnt lgkmcnt(1)
	v_mfma_f32_16x16x32_bf16 v[38:41], v[154:157], v[6:9], v[38:41]
	s_waitcnt lgkmcnt(0)
	v_mfma_f32_16x16x32_bf16 v[38:41], v[58:61], v[2:5], v[38:41]
	s_nop 0
	s_nop 6
	v_add_f32_e32 v34, v242, v38
	v_add_f32_e32 v35, v243, v39
	v_mul_f32_e32 v34, 0xbfb8aa3b, v34
	v_mul_f32_e32 v35, 0xbfb8aa3b, v35
	v_exp_f32_e32 v34, v34
	v_exp_f32_e32 v35, v35
	v_lshlrev_b32_e32 v38, 16, v56
	v_and_b32_e32 v39, 0xffff0000, v56
	v_pk_add_f32 v[34:35], v[34:35], 1.0 op_sel_hi:[1,0]
	s_nop 0
	v_rcp_f32_e32 v35, v35
	v_rcp_f32_e32 v34, v34
	s_nop 0
	v_pk_mul_f32 v[34:35], v[34:35], v[38:39]
	v_lshlrev_b32_e32 v38, 16, v57
	v_cvt_pk_bf16_f32 v34, v34, v35
	v_add_f32_e32 v35, v244, v40
	v_mul_f32_e32 v35, 0xbfb8aa3b, v35
	v_exp_f32_e32 v36, v35
	v_add_f32_e32 v35, v245, v41
	v_mul_f32_e32 v35, 0xbfb8aa3b, v35
	v_exp_f32_e32 v37, v35
	v_and_b32_e32 v39, 0xffff0000, v57
	v_pk_add_f32 v[36:37], v[36:37], 1.0 op_sel_hi:[1,0]
	s_nop 0
	v_rcp_f32_e32 v37, v37
	v_rcp_f32_e32 v36, v36
	s_nop 0
	v_pk_mul_f32 v[36:37], v[36:37], v[38:39]
	s_nop 0
	v_cvt_pk_bf16_f32 v35, v36, v37
	global_store_dwordx2 v[50:51], v[34:35], off offset:416
	ds_read_b128 v[38:41], v134
	ds_read_b128 v[56:59], v135
	ds_read_b128 v[150:153], v136
	ds_read_b128 v[154:157], v137
	s_waitcnt lgkmcnt(3)
	v_mfma_f32_16x16x32_bf16 v[38:41], v[38:41], v[30:33], 0
	s_waitcnt lgkmcnt(2)
	v_mfma_f32_16x16x32_bf16 v[38:41], v[56:59], v[26:29], v[38:41]
	ds_read_b128 v[56:59], v138
	s_waitcnt lgkmcnt(2)
	v_mfma_f32_16x16x32_bf16 v[38:41], v[150:153], v[22:25], v[38:41]
	ds_read_b128 v[150:153], v139
	s_waitcnt lgkmcnt(2)
	v_mfma_f32_16x16x32_bf16 v[38:41], v[154:157], v[18:21], v[38:41]
	ds_read_b128 v[154:157], v140
	s_waitcnt lgkmcnt(2)
	v_mfma_f32_16x16x32_bf16 v[38:41], v[56:59], v[14:17], v[38:41]
	ds_read_b128 v[56:59], v141
	s_waitcnt lgkmcnt(2)
	v_mfma_f32_16x16x32_bf16 v[38:41], v[150:153], v[10:13], v[38:41]
	s_waitcnt lgkmcnt(1)
	v_mfma_f32_16x16x32_bf16 v[38:41], v[154:157], v[6:9], v[38:41]
	s_waitcnt lgkmcnt(0)
	v_mfma_f32_16x16x32_bf16 v[38:41], v[56:59], v[2:5], v[38:41]
	s_nop 0
	s_nop 6
	v_add_f32_e32 v34, v246, v38
	v_add_f32_e32 v35, v247, v39
	v_mul_f32_e32 v34, 0xbfb8aa3b, v34
	v_mul_f32_e32 v35, 0xbfb8aa3b, v35
	v_exp_f32_e32 v34, v34
	v_exp_f32_e32 v35, v35
	v_lshlrev_b32_e32 v38, 16, v54
	v_and_b32_e32 v39, 0xffff0000, v54
	v_pk_add_f32 v[34:35], v[34:35], 1.0 op_sel_hi:[1,0]
	s_nop 0
	v_rcp_f32_e32 v35, v35
	v_rcp_f32_e32 v34, v34
	s_nop 0
	v_pk_mul_f32 v[34:35], v[34:35], v[38:39]
	v_lshlrev_b32_e32 v38, 16, v55
	v_cvt_pk_bf16_f32 v34, v34, v35
	v_add_f32_e32 v35, v248, v40
	v_mul_f32_e32 v35, 0xbfb8aa3b, v35
	v_exp_f32_e32 v36, v35
	v_add_f32_e32 v35, v249, v41
	v_mul_f32_e32 v35, 0xbfb8aa3b, v35
	v_exp_f32_e32 v37, v35
	v_and_b32_e32 v39, 0xffff0000, v55
	v_pk_add_f32 v[36:37], v[36:37], 1.0 op_sel_hi:[1,0]
	s_nop 0
	v_rcp_f32_e32 v37, v37
	v_rcp_f32_e32 v36, v36
	s_nop 0
	v_pk_mul_f32 v[36:37], v[36:37], v[38:39]
	s_nop 0
	v_cvt_pk_bf16_f32 v35, v36, v37
	global_store_dwordx2 v[50:51], v[34:35], off offset:448
	ds_read_b128 v[38:41], v142
	s_waitcnt lgkmcnt(0)
	v_mfma_f32_16x16x32_bf16 v[30:33], v[38:41], v[30:33], 0
	ds_read_b128 v[38:41], v143
	s_waitcnt lgkmcnt(0)
	v_mfma_f32_16x16x32_bf16 v[26:29], v[38:41], v[26:29], v[30:33]
	s_nop 4
	ds_read_b128 v[30:33], v144
	s_waitcnt lgkmcnt(0)
	v_mfma_f32_16x16x32_bf16 v[22:25], v[30:33], v[22:25], v[26:29]
	s_nop 2
	ds_read_b128 v[26:29], v145
	s_waitcnt lgkmcnt(0)
	v_mfma_f32_16x16x32_bf16 v[18:21], v[26:29], v[18:21], v[22:25]
	s_nop 2
	ds_read_b128 v[22:25], v146
	s_waitcnt lgkmcnt(0)
	v_mfma_f32_16x16x32_bf16 v[14:17], v[22:25], v[14:17], v[18:21]
	s_nop 2
	ds_read_b128 v[18:21], v147
	s_waitcnt lgkmcnt(0)
	v_mfma_f32_16x16x32_bf16 v[10:13], v[18:21], v[10:13], v[14:17]
	s_nop 2
	ds_read_b128 v[14:17], v148
	s_waitcnt lgkmcnt(0)
	v_mfma_f32_16x16x32_bf16 v[6:9], v[14:17], v[6:9], v[10:13]
	s_nop 2
	ds_read_b128 v[10:13], v149
	s_waitcnt lgkmcnt(0)
	v_mfma_f32_16x16x32_bf16 v[2:5], v[10:13], v[2:5], v[6:9]
	s_nop 2
	v_lshlrev_b32_e32 v6, 16, v52
	v_and_b32_e32 v7, 0xffff0000, v52
	s_nop 0
	s_nop 1
	v_add_f32_e32 v2, v250, v2
	v_add_f32_e32 v3, v251, v3
	v_mul_f32_e32 v2, 0xbfb8aa3b, v2
	v_mul_f32_e32 v3, 0xbfb8aa3b, v3
	v_exp_f32_e32 v2, v2
	v_exp_f32_e32 v3, v3
	s_nop 0
	v_pk_add_f32 v[2:3], v[2:3], 1.0 op_sel_hi:[1,0]
	s_nop 0
	v_rcp_f32_e32 v3, v3
	v_rcp_f32_e32 v2, v2
	s_nop 0
	v_pk_mul_f32 v[2:3], v[2:3], v[6:7]
	v_lshlrev_b32_e32 v6, 16, v53
	v_cvt_pk_bf16_f32 v2, v2, v3
	v_add_f32_e32 v3, v252, v4
	v_mul_f32_e32 v3, 0xbfb8aa3b, v3
	v_exp_f32_e32 v4, v3
	v_add_f32_e32 v3, v253, v5
	v_mul_f32_e32 v3, 0xbfb8aa3b, v3
	v_exp_f32_e32 v5, v3
	v_and_b32_e32 v7, 0xffff0000, v53
	v_pk_add_f32 v[4:5], v[4:5], 1.0 op_sel_hi:[1,0]
	s_nop 0
	v_rcp_f32_e32 v5, v5
	v_rcp_f32_e32 v4, v4
	s_nop 0
	v_pk_mul_f32 v[4:5], v[4:5], v[6:7]
	v_cmp_lt_i32_e32 vcc, s3, v84
	v_cvt_pk_bf16_f32 v3, v4, v5
	global_store_dwordx2 v[50:51], v[2:3], off offset:480
	s_or_b64 s[22:23], vcc, s[22:23]
	s_andn2_b64 exec, exec, s[22:23]
	s_cbranch_execnz .LBB0_298
.LBB0_299:
	s_or_b64 exec, exec, s[8:9]
	v_mov_b64_e32 v[150:151], 0x200
	v_mov_b64_e32 v[152:153], 0x1ff
	v_mov_b64_e32 v[154:155], 0x62f
	v_mov_b64_e32 v[156:157], 0x630
	s_mov_b64 s[2:3], 0
	s_barrier
